# mix part 2, layer 0: fourth-round fnet items on virtual blocks 16..39
# speedup vs baseline: 1.0034x; 1.0034x over previous
; DI void phase_mix(KP p, int l, char* lds) {
;     ...
;   for (int it = lb; it < e7; it += nlb) {
;     if (it >= e6) {
.Lperm_l0:
	s_add_i32 s46, s101, 48
	s_and_b32 s46, s46, 63
	s_addk_i32 s46, 0xc0
